# v23: attention d=4/16 partial stores widened to dwordx4 via permlane32_swap
# speedup vs baseline: 1.0039x; 1.0039x over previous
; __device__ __forceinline__ unsigned pk2(float lo, float hi) { return pg8::cvt_pk_bf16(lo, hi); }
; template <int MODE> ...
;     ...
;         const float lt0 = l + __shfl_xor(l, 32);
;         const size_t row = seqrow0 + (size_t)(q0 + r) * dil;
;         if (MODE == 0) {
; #pragma unroll
;             for (int dt = 0; dt < 2; ++dt)
; #pragma unroll
;                 for (int ii = 0; ii < 4; ++ii) { u32x2 w; w.x = pk2(o[dt][4 * ii], o[dt][4 * ii + 1]); w.y = pk2(o[dt][4 * ii + 2], o[dt][4 * ii + 3]);
;                     *(u32x2*)(Po + row * 512 + head * 64 + 32 * dt + 8 * ii + 4 * h) = w; }
;             if (h == 0) Lo[row * 8 + head] = lt0;
.LBB0_507:
	s_and_b64 s[0:1], s[88:89], exec
	s_mov_b32 s0, 0x15100000
	s_cselect_b32 s0, s0, 0x17100000
	s_add_u32 s0, s2, s0
	s_addc_u32 s1, s3, 0
	v_and_b32_e32 v33, 64, v132
	s_lshl_b32 s72, s76, 1
	v_xor_b32_e32 v32, 32, v132
	v_add_u32_e32 v33, 64, v33
	s_add_u32 s0, s0, s72
	v_cmp_lt_i32_e32 vcc, v32, v33
	s_addc_u32 s1, s1, 0
	v_lshlrev_b64 v[34:35], 10, v[96:97]
	v_cndmask_b32_e32 v32, v132, v32, vcc
	v_lshl_add_u64 v[34:35], s[0:1], 0, v[34:35]
	v_mov_b32_e32 v105, v97
	v_lshlrev_b32_e32 v32, 2, v32
	v_lshl_add_u64 v[34:35], v[34:35], 0, v[104:105]
	v_lshl_add_u64 v[34:35], v[34:35], 0, v[104:105]
	v_cvt_pk_bf16_f32 v16, v16, v17
	v_cvt_pk_bf16_f32 v17, v18, v19
	v_cvt_pk_bf16_f32 v18, v20, v21
	v_cvt_pk_bf16_f32 v19, v22, v23
	ds_bpermute_b32 v32, v32, v134
	s_nop 1
	v_permlane32_swap_b32_e32 v16, v18
	v_permlane32_swap_b32_e32 v17, v19
	global_store_dwordx4 v[34:35], v[16:19], off
	v_cvt_pk_bf16_f32 v20, v24, v25
	v_cvt_pk_bf16_f32 v21, v26, v27
	v_cvt_pk_bf16_f32 v22, v28, v29
	v_cvt_pk_bf16_f32 v23, v30, v31
	s_nop 1
	v_permlane32_swap_b32_e32 v20, v22
	v_permlane32_swap_b32_e32 v21, v23
	global_store_dwordx4 v[34:35], v[20:23], off offset:32
	v_cvt_pk_bf16_f32 v0, v0, v1
	v_cvt_pk_bf16_f32 v1, v2, v3
	v_cvt_pk_bf16_f32 v2, v4, v5
	v_cvt_pk_bf16_f32 v3, v6, v7
	s_nop 1
	v_permlane32_swap_b32_e32 v0, v2
	v_permlane32_swap_b32_e32 v1, v3
	global_store_dwordx4 v[34:35], v[0:3], off offset:64
	v_cvt_pk_bf16_f32 v4, v8, v9
	v_cvt_pk_bf16_f32 v5, v10, v11
	v_cvt_pk_bf16_f32 v6, v12, v13
	v_cvt_pk_bf16_f32 v7, v14, v15
	s_nop 1
	v_permlane32_swap_b32_e32 v4, v6
	v_permlane32_swap_b32_e32 v5, v7
	global_store_dwordx4 v[34:35], v[4:7], off offset:96
	s_and_saveexec_b64 s[0:1], s[70:71]
	s_cbranch_execz .LBB0_497
	s_and_b64 s[76:77], s[88:89], exec
	s_mov_b32 s72, 0x19100000
	s_cselect_b32 s72, s72, 0x19200000
	s_add_u32 s76, s2, s72
	s_addc_u32 s77, s3, 0
	v_lshlrev_b64 v[0:1], 5, v[96:97]
	v_lshl_add_u64 v[0:1], s[76:77], 0, v[0:1]
	s_lshl_b32 s72, s75, 2
	v_lshl_add_u64 v[0:1], v[0:1], 0, s[72:73]
	s_waitcnt lgkmcnt(0)
	v_add_f32_e32 v2, v134, v32
	global_store_dword v[0:1], v2, off
	s_branch .LBB0_497
